# v17 + phase-4 weight tiles respread: one per lower-half workgroup, two per upper-half workgroup (was three on the upper half only)
# speedup vs baseline: 1.0225x; 1.0009x over previous
.LBB0_419:
	v_ashrrev_i32_e32 v41, 31, v40
	v_lshlrev_b64 v[16:17], 11, v[40:41]
	s_waitcnt vmcnt(4)
	v_lshl_add_u64 v[32:33], v[36:37], 0, v[16:17]
	v_lshl_add_u64 v[16:17], v[38:39], 0, v[16:17]
	global_load_dwordx4 v[50:53], v[32:33], off
	global_load_dwordx4 v[54:57], v[16:17], off
	global_load_dwordx4 v[58:61], v[32:33], off offset:16
	global_load_dwordx4 v[62:65], v[16:17], off offset:16
	v_add_u32_e32 v16, 1, v40
	v_ashrrev_i32_e32 v17, 31, v16
	v_lshlrev_b64 v[16:17], 11, v[16:17]
	v_lshl_add_u64 v[48:49], v[36:37], 0, v[16:17]
	v_lshl_add_u64 v[16:17], v[38:39], 0, v[16:17]
	global_load_dwordx4 v[66:69], v[48:49], off offset:16
	global_load_dwordx4 v[70:73], v[48:49], off
	global_load_dwordx4 v[74:77], v[16:17], off offset:16
	global_load_dwordx4 v[78:81], v[16:17], off
	v_add_u32_e32 v18, 2, v40
	v_add_u32_e32 v20, 3, v40
	v_ashrrev_i32_e32 v19, 31, v18
	v_ashrrev_i32_e32 v21, 31, v20
	v_lshlrev_b64 v[18:19], 11, v[18:19]
	v_lshlrev_b64 v[20:21], 11, v[20:21]
	v_lshl_add_u64 v[46:47], v[36:37], 0, v[18:19]
	v_lshl_add_u64 v[82:83], v[38:39], 0, v[18:19]
	v_lshl_add_u64 v[44:45], v[36:37], 0, v[20:21]
	v_lshl_add_u64 v[34:35], v[38:39], 0, v[20:21]
	global_load_dwordx4 v[20:23], v[46:47], off offset:16
	global_load_dwordx4 v[28:31], v[46:47], off
	global_load_dwordx4 v[16:19], v[82:83], off offset:16
	global_load_dwordx4 v[24:27], v[82:83], off
	v_add_u32_e32 v40, s10, v40
	s_waitcnt vmcnt(10)
	v_lshlrev_b32_e32 v86, 16, v54
	v_lshlrev_b32_e32 v82, 16, v50
	v_and_b32_e32 v83, 0xffff0000, v50
	v_lshlrev_b32_e32 v84, 16, v52
	v_and_b32_e32 v85, 0xffff0000, v52
	v_and_b32_e32 v87, 0xffff0000, v54
	v_lshlrev_b32_e32 v88, 16, v56
	v_and_b32_e32 v89, 0xffff0000, v56
	s_waitcnt vmcnt(9)
	v_lshlrev_b32_e32 v90, 16, v58
	v_and_b32_e32 v91, 0xffff0000, v58
	v_lshlrev_b32_e32 v92, 16, v60
	v_and_b32_e32 v93, 0xffff0000, v60
	s_waitcnt vmcnt(8)
	v_lshlrev_b32_e32 v94, 16, v62
	v_and_b32_e32 v95, 0xffff0000, v62
	v_lshlrev_b32_e32 v96, 16, v64
	v_and_b32_e32 v97, 0xffff0000, v64
	v_lshlrev_b32_e32 v50, 16, v51
	v_and_b32_e32 v51, 0xffff0000, v51
	v_lshlrev_b32_e32 v54, 16, v55
	v_and_b32_e32 v55, 0xffff0000, v55
	v_lshlrev_b32_e32 v58, 16, v59
	v_and_b32_e32 v59, 0xffff0000, v59
	v_lshlrev_b32_e32 v62, 16, v63
	v_and_b32_e32 v63, 0xffff0000, v63
	v_pk_add_f32 v[82:83], v[82:83], v[86:87]
	v_pk_add_f32 v[84:85], v[84:85], v[88:89]
	v_pk_add_f32 v[90:91], v[90:91], v[94:95]
	v_pk_add_f32 v[92:93], v[92:93], v[96:97]
	v_lshlrev_b32_e32 v52, 16, v53
	v_and_b32_e32 v53, 0xffff0000, v53
	v_lshlrev_b32_e32 v56, 16, v57
	v_and_b32_e32 v57, 0xffff0000, v57
	v_lshlrev_b32_e32 v60, 16, v61
	v_and_b32_e32 v61, 0xffff0000, v61
	v_lshlrev_b32_e32 v64, 16, v65
	v_and_b32_e32 v65, 0xffff0000, v65
	v_pk_add_f32 v[50:51], v[50:51], v[54:55]
	v_pk_add_f32 v[88:89], v[58:59], v[62:63]
	v_mov_b32_e32 v54, v83
	v_mov_b32_e32 v55, v85
	v_mov_b32_e32 v62, v93
	v_mov_b32_e32 v63, v91
	v_pk_add_f32 v[86:87], v[52:53], v[56:57]
	v_pk_add_f32 v[94:95], v[60:61], v[64:65]
	v_mov_b32_e32 v52, v82
	v_mov_b32_e32 v53, v84
	v_mov_b32_e32 v60, v92
	v_mov_b32_e32 v61, v90
	v_pk_mul_f32 v[54:55], v[54:55], v[54:55]
	v_pk_mul_f32 v[62:63], v[62:63], v[62:63]
	v_mov_b32_e32 v56, v50
	v_mov_b32_e32 v57, v86
	v_mov_b32_e32 v64, v94
	v_pk_fma_f32 v[52:53], v[52:53], v[52:53], v[54:55]
	v_pk_fma_f32 v[54:55], v[60:61], v[60:61], v[62:63]
	v_mov_b32_e32 v65, v88
	v_mov_b32_e32 v58, v51
	v_mov_b32_e32 v59, v87
	v_pk_fma_f32 v[52:53], v[56:57], v[56:57], v[52:53]
	v_pk_fma_f32 v[54:55], v[64:65], v[64:65], v[54:55]
	v_mov_b32_e32 v56, v95
	v_mov_b32_e32 v57, v89
	v_pk_fma_f32 v[52:53], v[58:59], v[58:59], v[52:53]
	v_pk_fma_f32 v[54:55], v[56:57], v[56:57], v[54:55]
	s_waitcnt vmcnt(6)
	v_lshlrev_b32_e32 v56, 16, v70
	v_and_b32_e32 v57, 0xffff0000, v70
	v_lshlrev_b32_e32 v58, 16, v71
	v_and_b32_e32 v59, 0xffff0000, v71
	v_lshlrev_b32_e32 v60, 16, v72
	v_and_b32_e32 v61, 0xffff0000, v72
	v_lshlrev_b32_e32 v62, 16, v73
	v_and_b32_e32 v63, 0xffff0000, v73
	s_waitcnt vmcnt(4)
	v_lshlrev_b32_e32 v64, 16, v78
	v_and_b32_e32 v65, 0xffff0000, v78
	v_lshlrev_b32_e32 v70, 16, v79
	v_and_b32_e32 v71, 0xffff0000, v79
	v_lshlrev_b32_e32 v72, 16, v80
	v_and_b32_e32 v73, 0xffff0000, v80
	v_lshlrev_b32_e32 v78, 16, v81
	v_and_b32_e32 v79, 0xffff0000, v81
	v_pk_add_f32 v[80:81], v[58:59], v[70:71]
	v_pk_add_f32 v[96:97], v[56:57], v[64:65]
	v_pk_add_f32 v[72:73], v[60:61], v[72:73]
	v_lshlrev_b32_e32 v56, 16, v66
	v_and_b32_e32 v57, 0xffff0000, v66
	v_lshlrev_b32_e32 v58, 16, v67
	v_and_b32_e32 v59, 0xffff0000, v67
	v_lshlrev_b32_e32 v66, 16, v75
	v_and_b32_e32 v67, 0xffff0000, v75
	v_lshlrev_b32_e32 v64, 16, v74
	v_and_b32_e32 v65, 0xffff0000, v74
	v_pk_add_f32 v[74:75], v[58:59], v[66:67]
	v_mov_b32_e32 v58, v97
	v_mov_b32_e32 v59, v73
	v_pk_add_f32 v[78:79], v[62:63], v[78:79]
	v_lshlrev_b32_e32 v60, 16, v68
	v_and_b32_e32 v61, 0xffff0000, v68
	v_lshlrev_b32_e32 v62, 16, v69
	v_and_b32_e32 v63, 0xffff0000, v69
	v_lshlrev_b32_e32 v68, 16, v76
	v_and_b32_e32 v69, 0xffff0000, v76
	v_lshlrev_b32_e32 v70, 16, v77
	v_and_b32_e32 v71, 0xffff0000, v77
	v_pk_add_f32 v[76:77], v[56:57], v[64:65]
	v_mov_b32_e32 v56, v96
	v_mov_b32_e32 v57, v72
	v_pk_mul_f32 v[58:59], v[58:59], v[58:59]
	v_pk_add_f32 v[100:101], v[60:61], v[68:69]
	v_pk_fma_f32 v[56:57], v[56:57], v[56:57], v[58:59]
	v_mov_b32_e32 v58, v80
	v_mov_b32_e32 v59, v78
	v_pk_fma_f32 v[56:57], v[58:59], v[58:59], v[56:57]
	v_mov_b32_e32 v58, v81
	v_mov_b32_e32 v59, v79
	v_mov_b32_e32 v60, v101
	v_mov_b32_e32 v61, v77
	v_pk_add_f32 v[98:99], v[62:63], v[70:71]
	v_pk_fma_f32 v[56:57], v[58:59], v[58:59], v[56:57]
	v_mov_b32_e32 v58, v100
	v_mov_b32_e32 v59, v76
	v_pk_mul_f32 v[60:61], v[60:61], v[60:61]
	s_nop 0
	v_pk_fma_f32 v[58:59], v[58:59], v[58:59], v[60:61]
	v_mov_b32_e32 v60, v98
	v_mov_b32_e32 v61, v74
	v_pk_fma_f32 v[58:59], v[60:61], v[60:61], v[58:59]
	v_mov_b32_e32 v60, v99
	v_mov_b32_e32 v61, v75
	v_pk_fma_f32 v[58:59], v[60:61], v[60:61], v[58:59]
	v_mov_b32_e32 v60, v56
	v_mov_b32_e32 v61, v52
	v_mov_b32_e32 v52, v57
	v_pk_add_f32 v[52:53], v[60:61], v[52:53]
	v_mov_b32_e32 v56, v59
	v_mov_b32_e32 v57, v55
	v_pk_add_f32 v[52:53], v[52:53], v[56:57]
	v_mov_b32_e32 v59, v54
	v_pk_add_f32 v[52:53], v[58:59], v[52:53]
	s_nop 1
	v_mov_b32_dpp v55, v53 quad_perm:[1,0,3,2] row_mask:0xf bank_mask:0xf bound_ctrl:1
	v_mov_b32_dpp v54, v52 quad_perm:[1,0,3,2] row_mask:0xf bank_mask:0xf bound_ctrl:1
	v_pk_add_f32 v[52:53], v[52:53], v[54:55]
	s_nop 1
	v_mov_b32_dpp v55, v53 quad_perm:[2,3,0,1] row_mask:0xf bank_mask:0xf bound_ctrl:1
	v_mov_b32_dpp v54, v52 quad_perm:[2,3,0,1] row_mask:0xf bank_mask:0xf bound_ctrl:1
	v_pk_add_f32 v[52:53], v[52:53], v[54:55]
	s_nop 1
	v_mov_b32_dpp v55, v53 row_half_mirror row_mask:0xf bank_mask:0xf bound_ctrl:1
	v_mov_b32_dpp v54, v52 row_half_mirror row_mask:0xf bank_mask:0xf bound_ctrl:1
	v_pk_add_f32 v[52:53], v[52:53], v[54:55]
	s_nop 1
	v_mov_b32_dpp v55, v53 row_ror:8 row_mask:0xf bank_mask:0xf bound_ctrl:1
	v_mov_b32_dpp v54, v52 row_ror:8 row_mask:0xf bank_mask:0xf bound_ctrl:1
	v_pk_add_f32 v[52:53], v[52:53], v[54:55]
	s_nop 0
	v_pk_fma_f32 v[102:103], v[52:53], s[6:7], v[42:43] op_sel_hi:[1,0,0]
	global_load_dwordx4 v[52:55], v[44:45], off offset:16
	global_load_dwordx4 v[56:59], v[44:45], off
	global_load_dwordx4 v[60:63], v[34:35], off offset:16
	global_load_dwordx4 v[64:67], v[34:35], off
	v_mul_f32_e32 v41, 0x4b800000, v103
	v_cmp_gt_f32_e32 vcc, s11, v103
	s_nop 1
	v_cndmask_b32_e32 v41, v103, v41, vcc
	v_rsq_f32_e32 v41, v41
	s_nop 0
	v_mul_f32_e32 v34, 0x45800000, v41
	v_cndmask_b32_e32 v34, v41, v34, vcc
	v_pk_mul_f32 v[68:69], v[82:83], v[34:35] op_sel_hi:[1,0]
	v_pk_mul_f32 v[50:51], v[50:51], v[34:35] op_sel_hi:[1,0]
	v_pk_mul_f32 v[70:71], v[84:85], v[34:35] op_sel_hi:[1,0]
	v_pk_mul_f32 v[82:83], v[86:87], v[34:35] op_sel_hi:[1,0]
	v_pk_mul_f32 v[50:51], v[14:15], v[50:51]
	v_pk_mul_f32 v[68:69], v[12:13], v[68:69]
	v_pk_mul_f32 v[82:83], v[10:11], v[82:83]
	v_pk_mul_f32 v[70:71], v[8:9], v[70:71]
	v_mul_f32_e32 v41, 0x4b800000, v102
	v_cmp_gt_f32_e32 vcc, s11, v102
	v_cvt_pk_bf16_f32 v68, v68, v69
	v_cvt_pk_bf16_f32 v69, v50, v51
	v_cvt_pk_bf16_f32 v70, v70, v71
	v_cvt_pk_bf16_f32 v71, v82, v83
	v_cndmask_b32_e32 v41, v102, v41, vcc
	global_store_dwordx4 v[32:33], v[68:71], off
	v_rsq_f32_e32 v41, v41
	v_pk_mul_f32 v[50:51], v[90:91], v[34:35] op_sel_hi:[1,0]
	v_pk_mul_f32 v[68:69], v[88:89], v[34:35] op_sel_hi:[1,0]
	v_pk_mul_f32 v[50:51], v[4:5], v[50:51]
	v_pk_mul_f32 v[70:71], v[6:7], v[68:69]
	v_pk_mul_f32 v[68:69], v[92:93], v[34:35] op_sel_hi:[1,0]
	v_pk_mul_f32 v[34:35], v[94:95], v[34:35] op_sel_hi:[1,0]
	v_pk_mul_f32 v[82:83], v[0:1], v[68:69]
	v_pk_mul_f32 v[34:35], v[2:3], v[34:35]
	v_cvt_pk_bf16_f32 v68, v50, v51
	v_cvt_pk_bf16_f32 v69, v70, v71
	v_cvt_pk_bf16_f32 v70, v82, v83
	v_cvt_pk_bf16_f32 v71, v34, v35
	global_store_dwordx4 v[32:33], v[68:71], off offset:16
	v_mul_f32_e32 v32, 0x45800000, v41
	v_cndmask_b32_e32 v50, v41, v32, vcc
	v_pk_mul_f32 v[32:33], v[96:97], v[50:51] op_sel_hi:[1,0]
	v_pk_mul_f32 v[34:35], v[80:81], v[50:51] op_sel_hi:[1,0]
	v_pk_mul_f32 v[68:69], v[72:73], v[50:51] op_sel_hi:[1,0]
	v_pk_mul_f32 v[70:71], v[78:79], v[50:51] op_sel_hi:[1,0]
	v_pk_mul_f32 v[34:35], v[14:15], v[34:35]
	v_pk_mul_f32 v[32:33], v[12:13], v[32:33]
	v_pk_mul_f32 v[70:71], v[10:11], v[70:71]
	v_pk_mul_f32 v[68:69], v[8:9], v[68:69]
	v_cvt_pk_bf16_f32 v32, v32, v33
	v_cvt_pk_bf16_f32 v33, v34, v35
	v_cvt_pk_bf16_f32 v34, v68, v69
	v_cvt_pk_bf16_f32 v35, v70, v71
	global_store_dwordx4 v[48:49], v[32:35], off
	s_waitcnt vmcnt(9)
	v_lshlrev_b32_e32 v70, 16, v30
	v_and_b32_e32 v71, 0xffff0000, v30
	v_pk_mul_f32 v[32:33], v[76:77], v[50:51] op_sel_hi:[1,0]
	v_pk_mul_f32 v[34:35], v[74:75], v[50:51] op_sel_hi:[1,0]
	v_pk_mul_f32 v[32:33], v[4:5], v[32:33]
	v_pk_mul_f32 v[68:69], v[6:7], v[34:35]
	v_cvt_pk_bf16_f32 v32, v32, v33
	v_cvt_pk_bf16_f32 v33, v68, v69
	v_lshlrev_b32_e32 v68, 16, v28
	v_and_b32_e32 v69, 0xffff0000, v28
	v_lshlrev_b32_e32 v28, 16, v29
	v_and_b32_e32 v29, 0xffff0000, v29
	v_lshlrev_b32_e32 v30, 16, v31
	v_and_b32_e32 v31, 0xffff0000, v31
	s_waitcnt vmcnt(7)
	v_lshlrev_b32_e32 v72, 16, v24
	v_and_b32_e32 v73, 0xffff0000, v24
	v_lshlrev_b32_e32 v24, 16, v25
	v_and_b32_e32 v25, 0xffff0000, v25
	v_lshlrev_b32_e32 v74, 16, v26
	v_and_b32_e32 v75, 0xffff0000, v26
	v_lshlrev_b32_e32 v26, 16, v27
	v_and_b32_e32 v27, 0xffff0000, v27
	v_pk_add_f32 v[24:25], v[28:29], v[24:25]
	v_pk_add_f32 v[28:29], v[68:69], v[72:73]
	v_pk_add_f32 v[26:27], v[30:31], v[26:27]
	v_pk_add_f32 v[30:31], v[70:71], v[74:75]
	v_lshlrev_b32_e32 v70, 16, v22
	v_and_b32_e32 v71, 0xffff0000, v22
	v_lshlrev_b32_e32 v22, 16, v23
	v_and_b32_e32 v23, 0xffff0000, v23
	v_lshlrev_b32_e32 v74, 16, v18
	v_and_b32_e32 v75, 0xffff0000, v18
	v_lshlrev_b32_e32 v18, 16, v19
	v_and_b32_e32 v19, 0xffff0000, v19
	v_lshlrev_b32_e32 v68, 16, v20
	v_and_b32_e32 v69, 0xffff0000, v20
	v_lshlrev_b32_e32 v20, 16, v21
	v_and_b32_e32 v21, 0xffff0000, v21
	v_lshlrev_b32_e32 v72, 16, v16
	v_and_b32_e32 v73, 0xffff0000, v16
	v_lshlrev_b32_e32 v16, 16, v17
	v_and_b32_e32 v17, 0xffff0000, v17
	v_pk_add_f32 v[22:23], v[22:23], v[18:19]
	v_mov_b32_e32 v18, v29
	v_mov_b32_e32 v19, v31
	v_pk_add_f32 v[20:21], v[20:21], v[16:17]
	v_mov_b32_e32 v16, v28
	v_mov_b32_e32 v17, v30
	v_pk_mul_f32 v[18:19], v[18:19], v[18:19]
	v_pk_add_f32 v[68:69], v[68:69], v[72:73]
	v_pk_add_f32 v[70:71], v[70:71], v[74:75]
	v_pk_fma_f32 v[16:17], v[16:17], v[16:17], v[18:19]
	v_mov_b32_e32 v18, v24
	v_mov_b32_e32 v19, v26
	v_pk_fma_f32 v[16:17], v[18:19], v[18:19], v[16:17]
	v_mov_b32_e32 v18, v25
	v_mov_b32_e32 v19, v27
	v_mov_b32_e32 v72, v71
	v_mov_b32_e32 v73, v69
	v_pk_fma_f32 v[16:17], v[18:19], v[18:19], v[16:17]
	v_mov_b32_e32 v18, v70
	v_mov_b32_e32 v19, v68
	v_pk_mul_f32 v[72:73], v[72:73], v[72:73]
	s_waitcnt vmcnt(5)
	v_lshlrev_b32_e32 v74, 16, v58
	v_pk_fma_f32 v[18:19], v[18:19], v[18:19], v[72:73]
	v_mov_b32_e32 v72, v22
	v_mov_b32_e32 v73, v20
	v_pk_fma_f32 v[18:19], v[72:73], v[72:73], v[18:19]
	v_mov_b32_e32 v72, v23
	v_mov_b32_e32 v73, v21
	v_pk_fma_f32 v[18:19], v[72:73], v[72:73], v[18:19]
	v_lshlrev_b32_e32 v72, 16, v56
	v_and_b32_e32 v73, 0xffff0000, v56
	v_lshlrev_b32_e32 v56, 16, v57
	v_and_b32_e32 v57, 0xffff0000, v57
	v_and_b32_e32 v75, 0xffff0000, v58
	v_lshlrev_b32_e32 v58, 16, v59
	v_and_b32_e32 v59, 0xffff0000, v59
	s_waitcnt vmcnt(3)
	v_lshlrev_b32_e32 v76, 16, v64
	v_and_b32_e32 v77, 0xffff0000, v64
	v_lshlrev_b32_e32 v64, 16, v65
	v_and_b32_e32 v65, 0xffff0000, v65
	v_lshlrev_b32_e32 v78, 16, v66
	v_and_b32_e32 v79, 0xffff0000, v66
	v_lshlrev_b32_e32 v66, 16, v67
	v_and_b32_e32 v67, 0xffff0000, v67
	v_pk_add_f32 v[56:57], v[56:57], v[64:65]
	v_pk_add_f32 v[64:65], v[72:73], v[76:77]
	v_pk_add_f32 v[58:59], v[58:59], v[66:67]
	v_pk_add_f32 v[66:67], v[74:75], v[78:79]
	v_lshlrev_b32_e32 v74, 16, v54
	v_and_b32_e32 v75, 0xffff0000, v54
	v_lshlrev_b32_e32 v54, 16, v55
	v_and_b32_e32 v55, 0xffff0000, v55
	v_lshlrev_b32_e32 v78, 16, v62
	v_and_b32_e32 v79, 0xffff0000, v62
	v_lshlrev_b32_e32 v62, 16, v63
	v_and_b32_e32 v63, 0xffff0000, v63
	v_lshlrev_b32_e32 v72, 16, v52
	v_and_b32_e32 v73, 0xffff0000, v52
	v_lshlrev_b32_e32 v52, 16, v53
	v_and_b32_e32 v53, 0xffff0000, v53
	v_lshlrev_b32_e32 v76, 16, v60
	v_and_b32_e32 v77, 0xffff0000, v60
	v_lshlrev_b32_e32 v60, 16, v61
	v_and_b32_e32 v61, 0xffff0000, v61
	v_pk_add_f32 v[54:55], v[54:55], v[62:63]
	v_pk_add_f32 v[62:63], v[74:75], v[78:79]
	v_mov_b32_e32 v74, v65
	v_mov_b32_e32 v75, v67
	v_pk_add_f32 v[52:53], v[52:53], v[60:61]
	v_pk_add_f32 v[60:61], v[72:73], v[76:77]
	v_mov_b32_e32 v72, v64
	v_mov_b32_e32 v73, v66
	v_pk_mul_f32 v[74:75], v[74:75], v[74:75]
	v_mov_b32_e32 v76, v63
	v_pk_fma_f32 v[72:73], v[72:73], v[72:73], v[74:75]
	v_mov_b32_e32 v74, v56
	v_mov_b32_e32 v75, v58
	v_pk_fma_f32 v[72:73], v[74:75], v[74:75], v[72:73]
	v_mov_b32_e32 v74, v57
	v_mov_b32_e32 v75, v59
	v_mov_b32_e32 v77, v61
	v_pk_fma_f32 v[72:73], v[74:75], v[74:75], v[72:73]
	v_mov_b32_e32 v74, v62
	v_mov_b32_e32 v75, v60
	v_pk_mul_f32 v[76:77], v[76:77], v[76:77]
	v_pk_mul_f32 v[34:35], v[100:101], v[50:51] op_sel_hi:[1,0]
	v_pk_fma_f32 v[74:75], v[74:75], v[74:75], v[76:77]
	v_mov_b32_e32 v76, v54
	v_mov_b32_e32 v77, v52
	v_pk_fma_f32 v[74:75], v[76:77], v[76:77], v[74:75]
	v_mov_b32_e32 v76, v55
	v_mov_b32_e32 v77, v53
	v_pk_fma_f32 v[74:75], v[76:77], v[76:77], v[74:75]
	v_mov_b32_e32 v76, v72
	v_mov_b32_e32 v77, v16
	v_mov_b32_e32 v16, v73
	v_pk_add_f32 v[16:17], v[76:77], v[16:17]
	v_mov_b32_e32 v72, v75
	v_mov_b32_e32 v73, v19
	v_pk_add_f32 v[16:17], v[16:17], v[72:73]
	v_mov_b32_e32 v75, v18
	v_pk_add_f32 v[16:17], v[74:75], v[16:17]
	v_pk_mul_f32 v[50:51], v[98:99], v[50:51] op_sel_hi:[1,0]
	v_pk_mul_f32 v[34:35], v[0:1], v[34:35]
	v_mov_b32_dpp v19, v17 quad_perm:[1,0,3,2] row_mask:0xf bank_mask:0xf bound_ctrl:1
	v_mov_b32_dpp v18, v16 quad_perm:[1,0,3,2] row_mask:0xf bank_mask:0xf bound_ctrl:1
	v_pk_add_f32 v[16:17], v[16:17], v[18:19]
	v_pk_mul_f32 v[50:51], v[2:3], v[50:51]
	v_cvt_pk_bf16_f32 v34, v34, v35
	v_mov_b32_dpp v19, v17 quad_perm:[2,3,0,1] row_mask:0xf bank_mask:0xf bound_ctrl:1
	v_mov_b32_dpp v18, v16 quad_perm:[2,3,0,1] row_mask:0xf bank_mask:0xf bound_ctrl:1
	v_pk_add_f32 v[16:17], v[16:17], v[18:19]
	v_cvt_pk_bf16_f32 v35, v50, v51
	global_store_dwordx4 v[48:49], v[32:35], off offset:16
	v_mov_b32_dpp v19, v17 row_half_mirror row_mask:0xf bank_mask:0xf bound_ctrl:1
	v_mov_b32_dpp v18, v16 row_half_mirror row_mask:0xf bank_mask:0xf bound_ctrl:1
	v_pk_add_f32 v[16:17], v[16:17], v[18:19]
	s_nop 1
	v_mov_b32_dpp v19, v17 row_ror:8 row_mask:0xf bank_mask:0xf bound_ctrl:1
	v_mov_b32_dpp v18, v16 row_ror:8 row_mask:0xf bank_mask:0xf bound_ctrl:1
	v_pk_add_f32 v[16:17], v[16:17], v[18:19]
	v_mov_b64_e32 v[18:19], s[8:9]
	v_pk_fma_f32 v[72:73], v[16:17], s[6:7], v[18:19] op_sel_hi:[1,0,0]
	s_add_i32 s7, s7, s9
	v_mul_f32_e32 v16, 0x4b800000, v73
	v_cmp_gt_f32_e32 vcc, s11, v73
	s_cmpk_lt_i32 s7, 0x300
	s_nop 0
	v_cndmask_b32_e32 v16, v73, v16, vcc
	v_rsq_f32_e32 v16, v16
	s_nop 0
	v_mul_f32_e32 v17, 0x45800000, v16
	v_cndmask_b32_e32 v32, v16, v17, vcc
	v_pk_mul_f32 v[16:17], v[28:29], v[32:33] op_sel_hi:[1,0]
	v_pk_mul_f32 v[18:19], v[24:25], v[32:33] op_sel_hi:[1,0]
	v_pk_mul_f32 v[24:25], v[30:31], v[32:33] op_sel_hi:[1,0]
	v_pk_mul_f32 v[26:27], v[26:27], v[32:33] op_sel_hi:[1,0]
	v_pk_mul_f32 v[18:19], v[14:15], v[18:19]
	v_pk_mul_f32 v[16:17], v[12:13], v[16:17]
	v_pk_mul_f32 v[26:27], v[10:11], v[26:27]
	v_pk_mul_f32 v[24:25], v[8:9], v[24:25]
	v_cvt_pk_bf16_f32 v16, v16, v17
	v_cvt_pk_bf16_f32 v17, v18, v19
	v_cvt_pk_bf16_f32 v18, v24, v25
	v_cvt_pk_bf16_f32 v19, v26, v27
	global_store_dwordx4 v[46:47], v[16:19], off
	v_cmp_gt_f32_e32 vcc, s11, v72
	v_pk_mul_f32 v[22:23], v[22:23], v[32:33] op_sel_hi:[1,0]
	v_pk_mul_f32 v[16:17], v[68:69], v[32:33] op_sel_hi:[1,0]
	v_pk_mul_f32 v[18:19], v[20:21], v[32:33] op_sel_hi:[1,0]
	v_pk_mul_f32 v[16:17], v[4:5], v[16:17]
	v_pk_mul_f32 v[18:19], v[6:7], v[18:19]
	v_cvt_pk_bf16_f32 v16, v16, v17
	v_cvt_pk_bf16_f32 v17, v18, v19
	v_mul_f32_e32 v18, 0x4b800000, v72
	v_cndmask_b32_e32 v18, v72, v18, vcc
	v_rsq_f32_e32 v24, v18
	v_pk_mul_f32 v[20:21], v[70:71], v[32:33] op_sel_hi:[1,0]
	v_pk_mul_f32 v[22:23], v[2:3], v[22:23]
	v_pk_mul_f32 v[20:21], v[0:1], v[20:21]
	v_cvt_pk_bf16_f32 v19, v22, v23
	v_cvt_pk_bf16_f32 v18, v20, v21
	global_store_dwordx4 v[46:47], v[16:19], off offset:16
	s_nop 1
	v_mul_f32_e32 v16, 0x45800000, v24
	v_cndmask_b32_e32 v20, v24, v16, vcc
	v_pk_mul_f32 v[16:17], v[64:65], v[20:21] op_sel_hi:[1,0]
	v_pk_mul_f32 v[18:19], v[56:57], v[20:21] op_sel_hi:[1,0]
	v_pk_mul_f32 v[22:23], v[66:67], v[20:21] op_sel_hi:[1,0]
	v_pk_mul_f32 v[24:25], v[58:59], v[20:21] op_sel_hi:[1,0]
	v_pk_mul_f32 v[18:19], v[14:15], v[18:19]
	v_pk_mul_f32 v[16:17], v[12:13], v[16:17]
	v_pk_mul_f32 v[24:25], v[10:11], v[24:25]
	v_pk_mul_f32 v[22:23], v[8:9], v[22:23]
	v_cvt_pk_bf16_f32 v16, v16, v17
	v_cvt_pk_bf16_f32 v17, v18, v19
	v_cvt_pk_bf16_f32 v18, v22, v23
	v_cvt_pk_bf16_f32 v19, v24, v25
	global_store_dwordx4 v[44:45], v[16:19], off
	v_pk_mul_f32 v[22:23], v[62:63], v[20:21] op_sel_hi:[1,0]
	s_nop 0
	v_pk_mul_f32 v[16:17], v[60:61], v[20:21] op_sel_hi:[1,0]
	v_pk_mul_f32 v[18:19], v[52:53], v[20:21] op_sel_hi:[1,0]
	v_pk_mul_f32 v[20:21], v[54:55], v[20:21] op_sel_hi:[1,0]
	v_pk_mul_f32 v[18:19], v[6:7], v[18:19]
	v_pk_mul_f32 v[16:17], v[4:5], v[16:17]
	v_pk_mul_f32 v[20:21], v[2:3], v[20:21]
	v_pk_mul_f32 v[22:23], v[0:1], v[22:23]
	v_cvt_pk_bf16_f32 v16, v16, v17
	v_cvt_pk_bf16_f32 v17, v18, v19
	v_cvt_pk_bf16_f32 v18, v22, v23
	v_cvt_pk_bf16_f32 v19, v20, v21
	global_store_dwordx4 v[44:45], v[16:19], off offset:16
	s_cbranch_scc1 .LBB0_419
	s_branch .LBB0_420
.Lp4_low:
	s_cmp_eq_u32 s56, 0x100
	s_cbranch_scc0 .LBB0_432
	s_movk_i32 s98, 0x380
	s_mov_b32 s6, s2
	s_branch .Lp4_tiles
.LBB0_420:
	s_movk_i32 s98, 0x480
	s_sub_i32 s6, s2, s88
	s_cmp_eq_u32 s56, 0x100
	s_cbranch_scc0 .Lp4_tiles
	s_mov_b32 s6, s2
.Lp4_tiles:
	s_add_i32 s14, s6, 0x300
	s_cmp_ge_i32 s14, s98
	s_cbranch_scc1 .LBB0_432
	s_load_dwordx2 s[6:7], s[0:1], 0x108
	s_load_dwordx2 s[8:9], s[0:1], 0x50
	s_lshl_b32 s10, s56, 6
	s_lshl_b32 s11, s88, 6
	s_sub_i32 s16, s10, s11
	s_lshl_b32 s10, s56, 3
	s_lshl_b32 s11, s88, 3
	s_lshl_b32 s15, s14, 6
	s_lshl_b32 s17, s14, 3
	s_sub_i32 s18, s10, s11
	v_mov_b32_e32 v1, 0
	s_mov_b32 s19, 0x9040
	s_movk_i32 s20, 0x204
	s_branch .LBB0_423
.LBB0_422:
	s_ashr_i32 s11, s10, 31
	s_and_b32 s12, s15, 0x3c0
	s_waitcnt vmcnt(3)
	v_mov_b32_e32 v18, v234
	s_lshl_b64 s[10:11], s[10:11], 2
	s_waitcnt lgkmcnt(0)
	s_add_u32 s10, s8, s10
	v_lshlrev_b32_e32 v0, 4, v18
	s_addc_u32 s11, s9, s11
	v_and_b32_e32 v0, 0x1f0, v0
	v_ashrrev_i32_e32 v21, 5, v18
	v_lshl_add_u64 v[14:15], s[10:11], 0, v[0:1]
	v_add_u32_e32 v2, s12, v21
	v_mad_i64_i32 v[10:11], s[10:11], v2, s19, v[14:15]
	v_add_u32_e32 v2, 0x200, v18
	s_waitcnt vmcnt(2)
	v_ashrrev_i32_e32 v23, 5, v2
	v_add_u32_e32 v2, s12, v23
	v_mad_i64_i32 v[12:13], s[10:11], v2, s19, v[14:15]
	global_load_dwordx4 v[2:5], v[10:11], off
	global_load_dwordx4 v[6:9], v[12:13], off
	v_add_u32_e32 v10, 0x400, v18
	s_waitcnt vmcnt(3)
	v_ashrrev_i32_e32 v28, 5, v10
	v_add_u32_e32 v10, s12, v28
	v_add_u32_e32 v16, 0x600, v18
	v_mad_i64_i32 v[10:11], s[10:11], v10, s19, v[14:15]
	s_waitcnt vmcnt(2)
	v_ashrrev_i32_e32 v30, 5, v16
	global_load_dwordx4 v[10:13], v[10:11], off
	v_add_u32_e32 v16, s12, v30
	v_mad_i64_i32 v[14:15], s[10:11], v16, s19, v[14:15]
	global_load_dwordx4 v[14:17], v[14:15], off
	v_ashrrev_i32_e32 v19, 3, v18
	v_lshlrev_b32_e32 v18, 3, v18
	v_and_b32_e32 v22, 56, v18
	v_add_u32_e32 v20, 0, v0
	s_lshl_b32 s10, s12, 1
	v_lshlrev_b32_e32 v31, 2, v19
	v_mul_u32_u24_e32 v32, 0x204, v22
	v_mad_u64_u32 v[24:25], s[12:13], v21, s20, v[20:21]
	v_mad_u64_u32 v[26:27], s[12:13], v23, s20, v[20:21]
	v_mad_u64_u32 v[28:29], s[12:13], v28, s20, v[20:21]
	v_mad_u64_u32 v[20:21], s[12:13], v30, s20, v[20:21]
	s_add_u32 s10, s6, s10
	v_add3_u32 v21, 0, v32, v31
	v_lshlrev_b32_e32 v0, 1, v22
	s_addc_u32 s11, s7, 0
	v_add_u32_e32 v25, 12, v21
	v_lshl_add_u64 v[30:31], s[10:11], 0, v[0:1]
	v_add_u32_e32 v0, 8, v21
	v_add_u32_e32 v27, 16, v21
	v_add_u32_e32 v29, 20, v21
	v_add_u32_e32 v32, 24, v21
	v_add_u32_e32 v33, 28, v21
	v_add_u32_e32 v18, s21, v19
	v_ashrrev_i32_e32 v19, 31, v18
	v_add_u32_e32 v22, 64, v18
	v_lshlrev_b64 v[18:19], 11, v[18:19]
	v_ashrrev_i32_e32 v23, 31, v22
	v_lshl_add_u64 v[18:19], v[30:31], 0, v[18:19]
	s_sub_i32 s10, s14, s88
	s_add_i32 s14, s10, s56
	s_add_i32 s15, s15, s16
	s_add_i32 s17, s17, s18
	s_cmp_lt_i32 s14, s98
	s_waitcnt vmcnt(3)
	ds_write2_b32 v24, v2, v3 offset1:1
	ds_write2_b32 v24, v4, v5 offset0:2 offset1:3
	s_waitcnt vmcnt(2)
	ds_write2_b32 v26, v6, v7 offset1:1
	ds_write2_b32 v26, v8, v9 offset0:2 offset1:3
	s_waitcnt vmcnt(1)
	ds_write2_b32 v28, v10, v11 offset1:1
	ds_write2_b32 v28, v12, v13 offset0:2 offset1:3
	s_waitcnt vmcnt(0)
	ds_write2_b32 v20, v14, v15 offset1:1
	ds_write2_b32 v20, v16, v17 offset0:2 offset1:3
	s_waitcnt lgkmcnt(0)
	s_barrier
	ds_read2st64_b32 v[6:7], v21 offset1:1
	ds_read2_b32 v[8:9], v21 offset0:129 offset1:193
	ds_read2st64_b32 v[10:11], v0 offset0:4 offset1:5
	ds_read2st64_b32 v[12:13], v25 offset0:6 offset1:7
	ds_read2st64_b32 v[14:15], v27 offset0:8 offset1:9
	ds_read2st64_b32 v[16:17], v29 offset0:10 offset1:11
	ds_read2st64_b32 v[20:21], v32 offset0:12 offset1:13
	ds_read2st64_b32 v[24:25], v33 offset0:14 offset1:15
	s_waitcnt lgkmcnt(6)
	v_cvt_pk_bf16_f32 v2, v6, v8
	s_waitcnt lgkmcnt(4)
	v_cvt_pk_bf16_f32 v3, v10, v12
	s_waitcnt lgkmcnt(2)
	v_cvt_pk_bf16_f32 v4, v14, v16
	v_cvt_pk_bf16_f32 v6, v7, v9
	s_waitcnt lgkmcnt(0)
	v_cvt_pk_bf16_f32 v5, v20, v24
	global_store_dwordx4 v[18:19], v[2:5], off
	v_cvt_pk_bf16_f32 v7, v11, v13
	v_cvt_pk_bf16_f32 v8, v15, v17
	v_lshlrev_b64 v[2:3], 11, v[22:23]
	v_cvt_pk_bf16_f32 v9, v21, v25
	v_lshl_add_u64 v[2:3], v[30:31], 0, v[2:3]
	global_store_dwordx4 v[2:3], v[6:9], off
	s_barrier
	s_cbranch_scc0 .LBB0_432
